# prepA conv tasks: the join wait and the 27 conversions moved behind the 16 conv-weight loads (u-row loads and weight loads share one memory round trip)
# baseline (speedup 1.0000x reference)
; DI float bf2f(bf16_t b) { return __uint_as_float(((unsigned)b) << 16); }
; NI void prepA_row(const P& p, int l, int t0) {
;     ...
;       const int cbase = sg * 128 + ln, ucol = (islru ? O_BX : O_CQKV) + cbase, cwn = islru ? 512 : 1536;
;       const float* cw = (islru ? p.in[I_LCW] + (size_t)l * 4 * 512 : p.in[I_DCW] + (size_t)l * 4 * 1536) + cbase;
;       float u[RB + 3][4], w[4][4];
; #pragma unroll
;       for (int i = 0; i < RB + 3; ++i) {
;         const int rrow = t0 - 2 + i; const bool ok = rrow >= seg_lo && rrow < seg_hi;
; #pragma unroll
;         for (int j = 0; j < 4; ++j) u[i][j] = ok ? bf2f(U[(size_t)rrow * INP + ucol + 32 * j]) : 0.f;
;       }
; #pragma unroll
;       for (int tap = 0; tap < 4; ++tap)
; #pragma unroll
;         for (int j = 0; j < 4; ++j) w[tap][j] = cw[tap * cwn + 32 * j];
.LBB0_334:
	v_mov_b32_e32 v37, 0x200
	v_readlane_b32 s0, v255, 14
	v_cndmask_b32_e64 v42, v207, v37, s[24:25]
	s_nop 0
	s_nop 0
	v_mov_b32_e32 v37, s0
	v_readlane_b32 s0, v255, 16
	s_nop 0
	s_nop 0
	s_nop 0
	v_mov_b32_e32 v46, s0
	v_readlane_b32 s0, v255, 13
	v_cndmask_b32_e64 v51, v37, v46, s[24:25]
	s_nop 0
	v_mov_b32_e32 v37, s0
	v_readlane_b32 s0, v255, 15
	s_nop 1
	v_mov_b32_e32 v46, s0
	v_cndmask_b32_e64 v50, v37, v46, s[24:25]
	v_lshl_add_u64 v[52:53], v[96:97], 2, v[50:51]
	v_lshlrev_b32_e32 v50, 2, v42
	v_mov_b32_e32 v51, v97
	v_lshl_add_u64 v[60:61], v[52:53], 0, v[50:51]
	global_load_dword v56, v[52:53], off
	global_load_dword v57, v[52:53], off offset:128
	global_load_dword v37, v[52:53], off offset:256
	global_load_dword v50, v[52:53], off offset:384
	global_load_dword v58, v[60:61], off
	global_load_dword v59, v[60:61], off offset:128
	global_load_dword v46, v[60:61], off offset:256
	global_load_dword v51, v[60:61], off offset:384
	v_lshlrev_b32_e32 v60, 3, v42
	v_mov_b32_e32 v61, v97
	v_mul_u32_u24_e32 v42, 3, v42
	v_lshl_add_u64 v[62:63], v[52:53], 0, v[60:61]
	v_lshlrev_b32_e32 v60, 2, v42
	v_lshl_add_u64 v[78:79], v[52:53], 0, v[60:61]
	global_load_dword v60, v[62:63], off
	global_load_dword v61, v[62:63], off offset:128
	global_load_dword v80, v[62:63], off offset:256
	global_load_dword v52, v[62:63], off offset:384
	s_nop 0
	global_load_dword v62, v[78:79], off
	global_load_dword v63, v[78:79], off offset:128
	global_load_dword v81, v[78:79], off offset:256
	global_load_dword v53, v[78:79], off offset:384
	s_waitcnt vmcnt(16)
	v_lshlrev_b32_e32 v72, 16, v178
	v_lshlrev_b32_e32 v66, 16, v179
	v_lshlrev_b32_e32 v38, 16, v180
	v_lshlrev_b32_e32 v39, 16, v181
	v_lshlrev_b32_e32 v43, 16, v182
	v_lshlrev_b32_e32 v47, 16, v183
	v_lshlrev_b32_e32 v74, 16, v184
	v_lshlrev_b32_e32 v75, 16, v185
	v_lshlrev_b32_e32 v73, 16, v186
	v_lshlrev_b32_e32 v70, 16, v190
	v_lshlrev_b32_e32 v71, 16, v191
	v_lshlrev_b32_e32 v67, 16, v192
	v_lshlrev_b32_e32 v40, 16, v193
	v_lshlrev_b32_e32 v41, 16, v194
	v_lshlrev_b32_e32 v29, 16, v195
	v_lshlrev_b32_e32 v44, 16, v196
	v_lshlrev_b32_e32 v45, 16, v197
	v_lshlrev_b32_e32 v31, 16, v198
	v_lshlrev_b32_e32 v48, 16, v199
	v_lshlrev_b32_e32 v49, 16, v200
	v_lshlrev_b32_e32 v33, 16, v201
	v_lshlrev_b32_e32 v54, 16, v202
	v_lshlrev_b32_e32 v55, 16, v203
	v_lshlrev_b32_e32 v35, 16, v218
	v_lshlrev_b32_e32 v69, 16, v68
	v_lshlrev_b32_e32 v68, 16, v64
	v_lshlrev_b32_e32 v64, 16, v77
	v_lshlrev_b32_e32 v42, 16, v76
	s_and_saveexec_b64 s[0:1], s[22:23]
	s_xor_b64 s[0:1], exec, s[0:1]
	s_cbranch_execz .LBB0_344
; DI float siluf(float x) { return x / (1.f + __expf(-x)); }
; NI void prepA_row(const P& p, int l, int t0) {
;     ...
; #pragma unroll
;         for (int rr = 0; rr < RB; ++rr) {
;           float x[4]; float ss = 0.f;
; #pragma unroll
;           for (int j = 0; j < 4; ++j) {
;             float acc = 0.f;
; #pragma unroll
;             for (int tap = 0; tap < 4; ++tap) acc += w[tap][j] * u[rr + tap][j];
;             x[j] = siluf(acc); ss += x[j] * x[j];
;           }
;           if (sg < 8) {
;             ss = hw_sum(ss);
;             float sc = rsqrtf(ss + EPS); if (sg < 4) sc *= 0.08838834764831845f;
; #pragma unroll
;             for (int j = 0; j < 4; ++j) x[j] *= sc;
	s_waitcnt vmcnt(14)
	v_pk_fma_f32 v[74:75], v[74:75], v[56:57], 0 op_sel_hi:[1,1,0]
	v_cmp_gt_i32_e64 s[24:25], 8, v65
	s_waitcnt vmcnt(10)
	v_pk_fma_f32 v[74:75], v[70:71], v[58:59], v[74:75]
	v_cmp_gt_i32_e64 s[22:23], 4, v65
	s_waitcnt vmcnt(6)
	v_pk_fma_f32 v[74:75], v[60:61], v[68:69], v[74:75]
	s_waitcnt vmcnt(4)
	v_mov_b32_e32 v86, v52
	s_waitcnt vmcnt(2)
	v_pk_fma_f32 v[74:75], v[40:41], v[62:63], v[74:75]
	v_mov_b32_e32 v87, v38
	v_mul_f32_e32 v65, 0xbfb8aa3b, v74
	v_exp_f32_e32 v76, v65
	v_mul_f32_e32 v65, 0xbfb8aa3b, v75
	v_exp_f32_e32 v77, v65
	s_waitcnt vmcnt(1)
	v_mul_f32_e32 v84, v29, v81
	v_pk_add_f32 v[76:77], v[76:77], 1.0 op_sel_hi:[1,0]
	s_nop 0
	v_div_scale_f32 v65, s[48:49], v77, v77, v75
	v_rcp_f32_e32 v78, v65
	s_nop 0
	v_fma_f32 v79, -v65, v78, 1.0
	v_fmac_f32_e32 v78, v79, v78
	v_div_scale_f32 v79, vcc, v75, v77, v75
	v_mul_f32_e32 v82, v79, v78
	v_fma_f32 v83, -v65, v82, v79
	v_fmac_f32_e32 v82, v83, v78
	v_fma_f32 v65, -v65, v82, v79
	v_div_fmas_f32 v65, v65, v78, v82
	v_div_fixup_f32 v77, v65, v77, v75
	v_div_scale_f32 v65, s[48:49], v76, v76, v74
	v_rcp_f32_e32 v75, v65
	s_nop 0
	v_fma_f32 v78, -v65, v75, 1.0
	v_fmac_f32_e32 v75, v78, v75
	v_div_scale_f32 v78, vcc, v74, v76, v74
	v_mul_f32_e32 v79, v78, v75
	v_fma_f32 v82, -v65, v79, v78
	v_fmac_f32_e32 v79, v82, v75
	v_fma_f32 v65, -v65, v79, v78
	v_div_fmas_f32 v65, v65, v75, v79
	v_div_fixup_f32 v76, v65, v76, v74
	v_mul_f32_e32 v74, v73, v37
	v_mov_b32_e32 v73, v66
	v_pk_mul_f32 v[72:73], v[72:73], v[50:51]
	s_waitcnt vmcnt(0)
	v_mov_b32_e32 v65, v53
	v_mov_b32_e32 v75, v72
	v_mul_f32_e32 v78, v67, v46
	v_pk_mul_f32 v[86:87], v[86:87], v[64:65]
	v_pk_add_f32 v[74:75], v[74:75], 0 op_sel_hi:[1,0]
	v_mov_b32_e32 v79, v73
	v_mul_f32_e32 v82, v80, v42
	v_pk_add_f32 v[72:73], v[74:75], v[78:79]
	v_mov_b32_e32 v83, v86
	v_pk_add_f32 v[72:73], v[72:73], v[82:83]
	v_mov_b32_e32 v85, v87
	v_pk_add_f32 v[72:73], v[72:73], v[84:85]
	s_nop 0
	v_mul_f32_e32 v65, 0xbfb8aa3b, v72
	v_exp_f32_e32 v74, v65
	v_mul_f32_e32 v65, 0xbfb8aa3b, v73
	v_exp_f32_e32 v75, v65
	s_nop 0
	v_pk_add_f32 v[74:75], v[74:75], 1.0 op_sel_hi:[1,0]
	s_nop 0
	v_div_scale_f32 v65, s[48:49], v75, v75, v73
	v_rcp_f32_e32 v78, v65
	s_nop 0
	v_fma_f32 v79, -v65, v78, 1.0
	v_fmac_f32_e32 v78, v79, v78
	v_div_scale_f32 v79, vcc, v73, v75, v73
	v_mul_f32_e32 v82, v79, v78
	v_fma_f32 v83, -v65, v82, v79
	v_fmac_f32_e32 v82, v83, v78
	v_fma_f32 v65, -v65, v82, v79
	v_div_fmas_f32 v65, v65, v78, v82
	v_div_fixup_f32 v79, v65, v75, v73
	v_div_scale_f32 v65, s[48:49], v74, v74, v72
	v_rcp_f32_e32 v73, v65
	s_nop 0
	v_fma_f32 v75, -v65, v73, 1.0
	v_fmac_f32_e32 v73, v75, v73
	v_div_scale_f32 v75, vcc, v72, v74, v72
	v_mul_f32_e32 v78, v75, v73
	v_fma_f32 v82, -v65, v78, v75
	v_fmac_f32_e32 v78, v82, v73
	v_fma_f32 v65, -v65, v78, v75
	v_div_fmas_f32 v65, v65, v73, v78
	v_div_fixup_f32 v78, v65, v74, v72
	s_and_saveexec_b64 s[48:49], s[24:25]
	s_cbranch_execz .LBB0_337
	v_pk_mul_f32 v[72:73], v[76:77], v[76:77]
	v_pk_mul_f32 v[74:75], v[78:79], v[78:79]
	v_add_f32_e32 v65, v72, v73
	v_and_b32_e32 v73, 64, v210
	v_xor_b32_e32 v72, 16, v210
	v_add_u32_e32 v73, 64, v73
	v_cmp_lt_i32_e32 vcc, v72, v73
	v_add_f32_e32 v65, v65, v74
	v_add_f32_e32 v65, v65, v75
	v_cndmask_b32_e32 v72, v210, v72, vcc
	v_lshlrev_b32_e32 v72, 2, v72
	ds_bpermute_b32 v72, v72, v65
	s_waitcnt lgkmcnt(0)
	v_add_f32_e32 v65, v65, v72
	v_xor_b32_e32 v72, 8, v210
	v_cmp_lt_i32_e32 vcc, v72, v73
	s_nop 1
	v_cndmask_b32_e32 v72, v210, v72, vcc
	v_lshlrev_b32_e32 v72, 2, v72
	ds_bpermute_b32 v72, v72, v65
	s_waitcnt lgkmcnt(0)
	v_add_f32_e32 v65, v65, v72
	v_xor_b32_e32 v72, 4, v210
	v_cmp_lt_i32_e32 vcc, v72, v73
	s_nop 1
	v_cndmask_b32_e32 v72, v210, v72, vcc
	v_lshlrev_b32_e32 v72, 2, v72
	ds_bpermute_b32 v72, v72, v65
	s_waitcnt lgkmcnt(0)
	v_add_f32_e32 v65, v65, v72
	v_xor_b32_e32 v72, 2, v210
	v_cmp_lt_i32_e32 vcc, v72, v73
	s_nop 1
	v_cndmask_b32_e32 v72, v210, v72, vcc
	v_lshlrev_b32_e32 v72, 2, v72
	ds_bpermute_b32 v72, v72, v65
	s_waitcnt lgkmcnt(0)
	v_add_f32_e32 v65, v65, v72
	v_xor_b32_e32 v72, 1, v210
	v_cmp_lt_i32_e32 vcc, v72, v73
	s_nop 1
	v_cndmask_b32_e32 v72, v210, v72, vcc
	v_lshlrev_b32_e32 v72, 2, v72
	ds_bpermute_b32 v72, v72, v65
	s_waitcnt lgkmcnt(0)
	v_add_f32_e32 v65, v65, v72
	v_add_f32_e32 v65, 0x358637bd, v65
	v_mul_f32_e32 v72, 0x4b800000, v65
	v_cmp_gt_f32_e32 vcc, s77, v65
	s_nop 1
	v_cndmask_b32_e32 v65, v65, v72, vcc
	v_rsq_f32_e32 v65, v65
	s_nop 0
	v_mul_f32_e32 v72, 0x45800000, v65
	v_cndmask_b32_e32 v65, v65, v72, vcc
	v_mul_f32_e32 v72, 0x3db504f3, v65
	v_cndmask_b32_e64 v72, v65, v72, s[22:23]
	v_pk_mul_f32 v[78:79], v[78:79], v[72:73] op_sel_hi:[1,0]
	v_pk_mul_f32 v[76:77], v[76:77], v[72:73] op_sel_hi:[1,0]
